# gla branch projection epilogue rewritten: coalesced part/gate loads redistributed via LDS, next sub-tile in flight; attention epilogue gains hoisted; consolidated
# speedup vs baseline: 1.0227x; 1.0077x over previous
.LBB0_46:
	v_bfe_u32 v142, v0, 10, 10
	v_bfe_u32 v143, v0, 20, 10
	v_or3_b32 v0, v148, v142, v143
	v_cmp_eq_u32_e32 vcc, 0, v0
	s_waitcnt vmcnt(0)
	s_barrier
	s_and_saveexec_b64 s[0:1], vcc
	s_cbranch_execz .LBB0_56
	buffer_wbl2 sc1
	s_waitcnt vmcnt(0)
	s_add_u32 s4, s54, 0x322c080
	s_addc_u32 s5, s55, 0
	v_mov_b32_e32 v0, 0
	v_mov_b32_e32 v1, 1
	global_atomic_add v0, v1, s[4:5]

.LBB0_1119:
	s_or_b64 exec, exec, s[16:17]
	s_waitcnt vmcnt(0) lgkmcnt(0)
	s_barrier
	s_and_saveexec_b64 s[16:17], s[8:9]
	s_cbranch_execz .LBB0_1077
	v_div_scale_f32 v1, s[22:23], v84, v84, 1.0
	v_rcp_f32_e32 v2, v1
	s_ashr_i32 s22, s51, 9
	s_ashr_i32 s23, s22, 31
	s_lshl_b64 s[22:23], s[22:23], 24
	v_fma_f32 v3, -v1, v2, 1.0
	v_fmac_f32_e32 v2, v3, v2
	v_div_scale_f32 v3, vcc, 1.0, v84, 1.0
	v_mul_f32_e32 v4, v3, v2
	v_fma_f32 v5, -v1, v4, v3
	v_fmac_f32_e32 v4, v5, v2
	v_fma_f32 v1, -v1, v4, v3
	v_div_fmas_f32 v1, v1, v2, v4
	v_div_fixup_f32 v12, v1, v84, 1.0
	ds_read2st64_b32 v[14:15], v216 offset1:1
	ds_read2st64_b32 v[16:17], v216 offset0:2 offset1:3
	ds_read2st64_b32 v[18:19], v216 offset0:4 offset1:5
	ds_read2st64_b32 v[90:91], v216 offset0:6 offset1:7
	ds_read2st64_b32 v[92:93], v216 offset0:8 offset1:9
	ds_read2st64_b32 v[94:95], v216 offset0:10 offset1:11
	ds_read2st64_b32 v[96:97], v216 offset0:12 offset1:13
	ds_read2st64_b32 v[98:99], v216 offset0:14 offset1:15
	ds_read2st64_b32 v[100:101], v216 offset0:24 offset1:25
	ds_read2st64_b32 v[102:103], v216 offset0:26 offset1:27
	ds_read2st64_b32 v[2:3], v216 offset0:28 offset1:29
	ds_read2st64_b32 v[4:5], v216 offset0:30 offset1:31
	ds_read2st64_b32 v[104:105], v216 offset0:16 offset1:17
	ds_read2st64_b32 v[106:107], v216 offset0:18 offset1:19
	ds_read2st64_b32 v[108:109], v216 offset0:20 offset1:21
	ds_read2st64_b32 v[110:111], v216 offset0:22 offset1:23
	s_waitcnt lgkmcnt(5)
	v_pk_fma_f32 v[8:9], v[68:69], v[12:13], v[2:3] op_sel_hi:[1,0,1] neg_lo:[0,0,1] neg_hi:[0,0,1]
	s_waitcnt lgkmcnt(4)
	v_pk_fma_f32 v[10:11], v[70:71], v[12:13], v[4:5] op_sel_hi:[1,0,1] neg_lo:[0,0,1] neg_hi:[0,0,1]
	global_load_dwordx4 v[220:223], v[164:165], off
	global_load_dwordx4 v[224:227], v[164:165], off offset:64
	global_load_dwordx4 v[228:231], v[164:165], off offset:128
	global_load_dwordx4 v[232:235], v[164:165], off offset:192
	global_load_dwordx4 v[236:239], v[164:165], off offset:256
	global_load_dwordx4 v[240:243], v[164:165], off offset:320
	global_load_dwordx4 v[244:247], v[164:165], off offset:384
	global_load_dwordx4 v[248:251], v[164:165], off offset:448
	v_div_scale_f32 v1, s[42:43], v85, v85, 1.0
	v_rcp_f32_e32 v7, v1
	v_pk_fma_f32 v[70:71], v[82:83], v[12:13], v[16:17] op_sel_hi:[1,0,1] neg_lo:[0,0,1] neg_hi:[0,0,1]
	v_pk_fma_f32 v[80:81], v[80:81], v[12:13], v[14:15] op_sel_hi:[1,0,1] neg_lo:[0,0,1] neg_hi:[0,0,1]
	v_pk_fma_f32 v[78:79], v[78:79], v[12:13], v[90:91] op_sel_hi:[1,0,1] neg_lo:[0,0,1] neg_hi:[0,0,1]
	v_pk_fma_f32 v[76:77], v[76:77], v[12:13], v[18:19] op_sel_hi:[1,0,1] neg_lo:[0,0,1] neg_hi:[0,0,1]
	v_pk_fma_f32 v[68:69], v[74:75], v[12:13], v[94:95] op_sel_hi:[1,0,1] neg_lo:[0,0,1] neg_hi:[0,0,1]
	v_pk_fma_f32 v[72:73], v[72:73], v[12:13], v[92:93] op_sel_hi:[1,0,1] neg_lo:[0,0,1] neg_hi:[0,0,1]
	v_pk_fma_f32 v[66:67], v[66:67], v[12:13], v[98:99] op_sel_hi:[1,0,1] neg_lo:[0,0,1] neg_hi:[0,0,1]
	v_pk_fma_f32 v[64:65], v[64:65], v[12:13], v[96:97] op_sel_hi:[1,0,1] neg_lo:[0,0,1] neg_hi:[0,0,1]
	s_waitcnt lgkmcnt(2)
	v_pk_fma_f32 v[62:63], v[62:63], v[12:13], v[106:107] op_sel_hi:[1,0,1] neg_lo:[0,0,1] neg_hi:[0,0,1]
	v_pk_fma_f32 v[60:61], v[60:61], v[12:13], v[104:105] op_sel_hi:[1,0,1] neg_lo:[0,0,1] neg_hi:[0,0,1]
	s_waitcnt lgkmcnt(0)
	v_pk_fma_f32 v[18:19], v[58:59], v[12:13], v[110:111] op_sel_hi:[1,0,1] neg_lo:[0,0,1] neg_hi:[0,0,1]
	v_pk_fma_f32 v[56:57], v[56:57], v[12:13], v[108:109] op_sel_hi:[1,0,1] neg_lo:[0,0,1] neg_hi:[0,0,1]
	v_pk_fma_f32 v[16:17], v[54:55], v[12:13], v[102:103] op_sel_hi:[1,0,1] neg_lo:[0,0,1] neg_hi:[0,0,1]
	v_pk_fma_f32 v[52:53], v[52:53], v[12:13], v[100:101] op_sel_hi:[1,0,1] neg_lo:[0,0,1] neg_hi:[0,0,1]
	v_fma_f32 v12, -v1, v7, 1.0
	v_fmac_f32_e32 v7, v12, v7
	v_div_scale_f32 v12, vcc, 1.0, v85, 1.0
	v_mul_f32_e32 v13, v12, v7
	v_fma_f32 v14, -v1, v13, v12
	v_fmac_f32_e32 v13, v14, v7
	v_fma_f32 v1, -v1, v13, v12
	v_div_fmas_f32 v1, v1, v7, v13
	v_div_fixup_f32 v74, v1, v85, 1.0
	ds_read2st64_b32 v[82:83], v216 offset0:32 offset1:33
	ds_read2st64_b32 v[84:85], v216 offset0:34 offset1:35
	ds_read2st64_b32 v[90:91], v216 offset0:36 offset1:37
	ds_read2st64_b32 v[92:93], v216 offset0:38 offset1:39
	ds_read2st64_b32 v[94:95], v216 offset0:40 offset1:41
	ds_read2st64_b32 v[96:97], v216 offset0:42 offset1:43
	ds_read2st64_b32 v[98:99], v216 offset0:44 offset1:45
	ds_read2st64_b32 v[100:101], v216 offset0:46 offset1:47
	ds_read2st64_b32 v[102:103], v216 offset0:56 offset1:57
	ds_read2st64_b32 v[104:105], v216 offset0:58 offset1:59
	ds_read2st64_b32 v[12:13], v216 offset0:60 offset1:61
	ds_read2st64_b32 v[14:15], v216 offset0:62 offset1:63
	ds_read2st64_b32 v[106:107], v216 offset0:48 offset1:49
	ds_read2st64_b32 v[108:109], v216 offset0:50 offset1:51
	ds_read2st64_b32 v[110:111], v216 offset0:52 offset1:53
	ds_read2st64_b32 v[112:113], v216 offset0:54 offset1:55
	s_waitcnt lgkmcnt(14)
	v_pk_fma_f32 v[48:49], v[48:49], v[74:75], v[82:83] op_sel_hi:[1,0,1] neg_lo:[0,0,1] neg_hi:[0,0,1]
	s_waitcnt lgkmcnt(5)
	v_pk_fma_f32 v[12:13], v[36:37], v[74:75], v[12:13] op_sel_hi:[1,0,1] neg_lo:[0,0,1] neg_hi:[0,0,1]
	v_pk_fma_f32 v[36:37], v[50:51], v[74:75], v[84:85] op_sel_hi:[1,0,1] neg_lo:[0,0,1] neg_hi:[0,0,1]
	v_mov_b32_e32 v84, v49
	v_mov_b32_e32 v85, v81
	v_mov_b32_e32 v82, v48
	v_mov_b32_e32 v83, v80
	v_pk_mul_f32 v[84:85], v[84:85], v[84:85]
	s_waitcnt lgkmcnt(4)
	v_pk_fma_f32 v[14:15], v[38:39], v[74:75], v[14:15] op_sel_hi:[1,0,1] neg_lo:[0,0,1] neg_hi:[0,0,1]
	v_mov_b32_e32 v38, v36
	v_mov_b32_e32 v39, v70
	v_pk_fma_f32 v[82:83], v[82:83], v[82:83], v[84:85]
	v_mov_b32_e32 v50, v37
	v_mov_b32_e32 v51, v71
	v_pk_fma_f32 v[82:83], v[38:39], v[38:39], v[82:83]
	v_pk_fma_f32 v[44:45], v[44:45], v[74:75], v[90:91] op_sel_hi:[1,0,1] neg_lo:[0,0,1] neg_hi:[0,0,1]
	v_pk_fma_f32 v[50:51], v[50:51], v[50:51], v[82:83]
	v_mov_b32_e32 v90, v44
	v_mov_b32_e32 v91, v76
	v_pk_fma_f32 v[46:47], v[46:47], v[74:75], v[92:93] op_sel_hi:[1,0,1] neg_lo:[0,0,1] neg_hi:[0,0,1]
	v_mov_b32_e32 v92, v45
	v_mov_b32_e32 v93, v77
	v_pk_fma_f32 v[50:51], v[90:91], v[90:91], v[50:51]
	v_mov_b32_e32 v82, v46
	v_mov_b32_e32 v83, v78
	v_pk_fma_f32 v[50:51], v[92:93], v[92:93], v[50:51]
	v_pk_fma_f32 v[40:41], v[40:41], v[74:75], v[94:95] op_sel_hi:[1,0,1] neg_lo:[0,0,1] neg_hi:[0,0,1]
	v_mov_b32_e32 v84, v47
	v_mov_b32_e32 v85, v79
	v_pk_fma_f32 v[50:51], v[82:83], v[82:83], v[50:51]
	v_mov_b32_e32 v90, v40
	v_pk_fma_f32 v[50:51], v[84:85], v[84:85], v[50:51]
	v_mov_b32_e32 v91, v72
	v_pk_fma_f32 v[38:39], v[42:43], v[74:75], v[96:97] op_sel_hi:[1,0,1] neg_lo:[0,0,1] neg_hi:[0,0,1]
	v_mov_b32_e32 v92, v41
	v_mov_b32_e32 v93, v73
	v_pk_fma_f32 v[50:51], v[90:91], v[90:91], v[50:51]
	v_mov_b32_e32 v82, v38
	v_mov_b32_e32 v83, v68
	v_pk_fma_f32 v[50:51], v[92:93], v[92:93], v[50:51]
	v_pk_fma_f32 v[32:33], v[32:33], v[74:75], v[98:99] op_sel_hi:[1,0,1] neg_lo:[0,0,1] neg_hi:[0,0,1]
	v_mov_b32_e32 v84, v39
	v_mov_b32_e32 v85, v69
	v_pk_fma_f32 v[50:51], v[82:83], v[82:83], v[50:51]
	v_mov_b32_e32 v82, v32
	v_pk_fma_f32 v[50:51], v[84:85], v[84:85], v[50:51]
	v_mov_b32_e32 v83, v64
	v_pk_fma_f32 v[34:35], v[34:35], v[74:75], v[100:101] op_sel_hi:[1,0,1] neg_lo:[0,0,1] neg_hi:[0,0,1]
	v_mov_b32_e32 v84, v33
	v_mov_b32_e32 v85, v65
	v_pk_fma_f32 v[50:51], v[82:83], v[82:83], v[50:51]
	v_mov_b32_e32 v42, v34
	v_mov_b32_e32 v43, v66
	v_pk_fma_f32 v[50:51], v[84:85], v[84:85], v[50:51]
	s_waitcnt lgkmcnt(3)
	v_pk_fma_f32 v[28:29], v[28:29], v[74:75], v[106:107] op_sel_hi:[1,0,1] neg_lo:[0,0,1] neg_hi:[0,0,1]
	v_mov_b32_e32 v84, v35
	v_mov_b32_e32 v85, v67
	v_pk_fma_f32 v[42:43], v[42:43], v[42:43], v[50:51]
	v_mov_b32_e32 v90, v28
	v_pk_fma_f32 v[42:43], v[84:85], v[84:85], v[42:43]
	v_mov_b32_e32 v91, v60
	s_waitcnt lgkmcnt(2)
	v_pk_fma_f32 v[30:31], v[30:31], v[74:75], v[108:109] op_sel_hi:[1,0,1] neg_lo:[0,0,1] neg_hi:[0,0,1]
	v_mov_b32_e32 v92, v29
	v_mov_b32_e32 v93, v61
	v_pk_fma_f32 v[42:43], v[90:91], v[90:91], v[42:43]
	v_mov_b32_e32 v50, v30
	v_mov_b32_e32 v51, v62
	v_pk_fma_f32 v[42:43], v[92:93], v[92:93], v[42:43]
	s_waitcnt lgkmcnt(1)
	v_pk_fma_f32 v[24:25], v[24:25], v[74:75], v[110:111] op_sel_hi:[1,0,1] neg_lo:[0,0,1] neg_hi:[0,0,1]
	v_mov_b32_e32 v84, v31
	v_mov_b32_e32 v85, v63
	v_pk_fma_f32 v[42:43], v[50:51], v[50:51], v[42:43]
	v_mov_b32_e32 v90, v24
	v_pk_fma_f32 v[42:43], v[84:85], v[84:85], v[42:43]
	v_mov_b32_e32 v91, v56
	s_waitcnt lgkmcnt(0)
	v_pk_fma_f32 v[26:27], v[26:27], v[74:75], v[112:113] op_sel_hi:[1,0,1] neg_lo:[0,0,1] neg_hi:[0,0,1]
	v_mov_b32_e32 v92, v25
	v_mov_b32_e32 v93, v57
	v_pk_fma_f32 v[42:43], v[90:91], v[90:91], v[42:43]
	v_pk_fma_f32 v[20:21], v[20:21], v[74:75], v[102:103] op_sel_hi:[1,0,1] neg_lo:[0,0,1] neg_hi:[0,0,1]
	v_mov_b32_e32 v50, v26
	v_mov_b32_e32 v51, v18
	v_pk_fma_f32 v[42:43], v[92:93], v[92:93], v[42:43]
	v_pk_mul_f32 v[58:59], v[52:53], v[52:53]
	v_pk_fma_f32 v[22:23], v[22:23], v[74:75], v[104:105] op_sel_hi:[1,0,1] neg_lo:[0,0,1] neg_hi:[0,0,1]
	v_pk_mul_f32 v[74:75], v[20:21], v[20:21]
	v_mov_b32_e32 v84, v27
	v_mov_b32_e32 v85, v19
	v_pk_fma_f32 v[42:43], v[50:51], v[50:51], v[42:43]
	v_mov_b32_e32 v50, v74
	v_pk_fma_f32 v[42:43], v[84:85], v[84:85], v[42:43]
	v_mov_b32_e32 v51, v58
	v_pk_mul_f32 v[54:55], v[16:17], v[16:17]
	v_pk_mul_f32 v[82:83], v[22:23], v[22:23]
	v_pk_add_f32 v[42:43], v[42:43], v[50:51]
	v_mov_b32_e32 v58, v75
	v_pk_add_f32 v[42:43], v[42:43], v[58:59]
	v_mov_b32_e32 v50, v82
	v_mov_b32_e32 v51, v54
	v_pk_mul_f32 v[88:89], v[8:9], v[8:9]
	v_pk_mul_f32 v[114:115], v[12:13], v[12:13]
	v_pk_add_f32 v[42:43], v[42:43], v[50:51]
	v_mov_b32_e32 v54, v83
	v_pk_add_f32 v[42:43], v[42:43], v[54:55]
	v_mov_b32_e32 v50, v114
	v_mov_b32_e32 v51, v88
	v_pk_mul_f32 v[86:87], v[10:11], v[10:11]
	v_pk_mul_f32 v[116:117], v[14:15], v[14:15]
	v_pk_add_f32 v[42:43], v[42:43], v[50:51]
	v_mov_b32_e32 v88, v115
	v_pk_add_f32 v[42:43], v[42:43], v[88:89]
	v_mov_b32_e32 v50, v116
	v_mov_b32_e32 v51, v86
	v_pk_add_f32 v[42:43], v[42:43], v[50:51]
	v_mov_b32_e32 v86, v117
	v_pk_add_f32 v[42:43], v[42:43], v[86:87]
	ds_bpermute_b32 v51, v198, v43
	ds_bpermute_b32 v50, v198, v42
	s_add_u32 s18, s58, s22
	s_addc_u32 s21, s59, s23
	s_lshl_b32 s22, s49, 8
	s_add_u32 s22, s18, s22
	s_waitcnt lgkmcnt(0)
	v_pk_add_f32 v[42:43], v[42:43], v[50:51]
	ds_bpermute_b32 v51, v199, v43
	ds_bpermute_b32 v50, v199, v42
	s_brev_b32 s18, 60
	v_add_u32_e32 v6, s38, v156
	v_ashrrev_i32_e32 v7, 31, v6
	v_lshlrev_b64 v[54:55], 11, v[6:7]
	s_waitcnt lgkmcnt(0)
	v_pk_add_f32 v[42:43], v[42:43], v[50:51]
	v_mov_b32_e32 v50, 0x358637bd
	v_pk_fma_f32 v[42:43], v[42:43], s[18:19], v[50:51] op_sel_hi:[1,0,0]
	s_addc_u32 s23, s21, 0
	v_mul_f32_e32 v1, 0x4b800000, v43
	v_cmp_gt_f32_e32 vcc, s47, v43
	v_lshl_add_u64 v[50:51], s[22:23], 0, v[54:55]
	v_mov_b32_e32 v173, v0
	v_cndmask_b32_e32 v1, v43, v1, vcc
	v_rsq_f32_e32 v1, v1
	v_lshl_add_u64 v[50:51], v[50:51], 0, v[172:173]
	v_or_b32_e32 v6, 16, v6
	v_mul_f32_e32 v7, 0x45800000, v1
	v_cndmask_b32_e32 v1, v1, v7, vcc
	v_mul_f32_e32 v54, 0x3f4ccccd, v1
	v_pk_mul_f32 v[58:59], v[80:81], v[54:55] op_sel_hi:[1,0]
	v_pk_mul_f32 v[68:69], v[68:69], v[54:55] op_sel_hi:[1,0]
	s_waitcnt vmcnt(0)
	v_pk_mul_f32 v[2:3], v[220:221], v[58:59]
	v_pk_mul_f32 v[58:59], v[70:71], v[54:55] op_sel_hi:[1,0]
	v_cvt_pk_bf16_f32 v2, v2, v3
	v_pk_mul_f32 v[4:5], v[222:223], v[58:59]
	v_pk_mul_f32 v[58:59], v[76:77], v[54:55] op_sel_hi:[1,0]
	v_cvt_pk_bf16_f32 v3, v4, v5
	global_store_dwordx2 v[50:51], v[2:3], off
	v_pk_mul_f32 v[56:57], v[56:57], v[54:55] op_sel_hi:[1,0]
	v_pk_mul_f32 v[18:19], v[18:19], v[54:55] op_sel_hi:[1,0]
	v_pk_mul_f32 v[16:17], v[16:17], v[54:55] op_sel_hi:[1,0]
	v_pk_mul_f32 v[8:9], v[8:9], v[54:55] op_sel_hi:[1,0]
	v_pk_mul_f32 v[10:11], v[10:11], v[54:55] op_sel_hi:[1,0]
	v_mul_f32_e32 v1, 0x4b800000, v42
	v_cmp_gt_f32_e32 vcc, s47, v42
	v_ashrrev_i32_e32 v7, 31, v6
	v_lshlrev_b64 v[6:7], 11, v[6:7]
	v_cndmask_b32_e32 v1, v42, v1, vcc
	v_rsq_f32_e32 v1, v1
	v_lshl_add_u64 v[6:7], s[22:23], 0, v[6:7]
	v_lshl_add_u64 v[6:7], v[6:7], 0, v[172:173]
	v_pk_mul_f32 v[2:3], v[224:225], v[58:59]
	v_pk_mul_f32 v[58:59], v[78:79], v[54:55] op_sel_hi:[1,0]
	v_cvt_pk_bf16_f32 v2, v2, v3
	v_pk_mul_f32 v[4:5], v[226:227], v[58:59]
	v_pk_mul_f32 v[58:59], v[72:73], v[54:55] op_sel_hi:[1,0]
	v_cvt_pk_bf16_f32 v3, v4, v5
	global_store_dwordx2 v[50:51], v[2:3], off offset:32
	v_pk_mul_f32 v[2:3], v[228:229], v[58:59]
	v_pk_mul_f32 v[4:5], v[230:231], v[68:69]
	v_cvt_pk_bf16_f32 v2, v2, v3
	v_cvt_pk_bf16_f32 v3, v4, v5
	global_store_dwordx2 v[50:51], v[2:3], off offset:64
	v_pk_mul_f32 v[58:59], v[64:65], v[54:55] op_sel_hi:[1,0]
	v_pk_mul_f32 v[64:65], v[66:67], v[54:55] op_sel_hi:[1,0]
	v_pk_mul_f32 v[2:3], v[232:233], v[58:59]
	v_pk_mul_f32 v[4:5], v[234:235], v[64:65]
	v_cvt_pk_bf16_f32 v2, v2, v3
	v_cvt_pk_bf16_f32 v3, v4, v5
	global_store_dwordx2 v[50:51], v[2:3], off offset:96
	v_pk_mul_f32 v[58:59], v[60:61], v[54:55] op_sel_hi:[1,0]
	v_pk_mul_f32 v[60:61], v[62:63], v[54:55] op_sel_hi:[1,0]
	v_pk_mul_f32 v[2:3], v[58:59], v[236:237]
	v_pk_mul_f32 v[4:5], v[60:61], v[238:239]
	v_cvt_pk_bf16_f32 v2, v2, v3
	v_cvt_pk_bf16_f32 v3, v4, v5
	global_store_dwordx2 v[50:51], v[2:3], off offset:128
	v_pk_mul_f32 v[2:3], v[56:57], v[240:241]
	v_pk_mul_f32 v[4:5], v[18:19], v[242:243]
	v_cvt_pk_bf16_f32 v2, v2, v3
	v_cvt_pk_bf16_f32 v3, v4, v5
	global_store_dwordx2 v[50:51], v[2:3], off offset:160
	v_pk_mul_f32 v[18:19], v[52:53], v[54:55] op_sel_hi:[1,0]
	v_pk_mul_f32 v[4:5], v[16:17], v[246:247]
	v_pk_mul_f32 v[2:3], v[18:19], v[244:245]
	s_nop 0
	v_cvt_pk_bf16_f32 v2, v2, v3
	v_cvt_pk_bf16_f32 v3, v4, v5
	global_store_dwordx2 v[50:51], v[2:3], off offset:192
	v_pk_mul_f32 v[2:3], v[8:9], v[248:249]
	v_pk_mul_f32 v[4:5], v[10:11], v[250:251]
	v_cvt_pk_bf16_f32 v2, v2, v3
	v_cvt_pk_bf16_f32 v3, v4, v5
	global_store_dwordx2 v[50:51], v[2:3], off offset:224
	v_mul_f32_e32 v8, 0x45800000, v1
	v_cndmask_b32_e32 v1, v1, v8, vcc
	v_mul_f32_e32 v8, 0x3f4ccccd, v1
	v_pk_mul_f32 v[10:11], v[48:49], v[8:9] op_sel_hi:[1,0]
	v_pk_mul_f32 v[16:17], v[36:37], v[8:9] op_sel_hi:[1,0]
	v_pk_mul_f32 v[2:3], v[220:221], v[10:11]
	v_pk_mul_f32 v[4:5], v[222:223], v[16:17]
	v_cvt_pk_bf16_f32 v2, v2, v3
	v_cvt_pk_bf16_f32 v3, v4, v5
	global_store_dwordx2 v[6:7], v[2:3], off
	v_pk_mul_f32 v[10:11], v[44:45], v[8:9] op_sel_hi:[1,0]
	v_pk_mul_f32 v[16:17], v[46:47], v[8:9] op_sel_hi:[1,0]
	v_pk_mul_f32 v[2:3], v[224:225], v[10:11]
	v_pk_mul_f32 v[4:5], v[226:227], v[16:17]
	v_cvt_pk_bf16_f32 v2, v2, v3
	v_cvt_pk_bf16_f32 v3, v4, v5
	global_store_dwordx2 v[6:7], v[2:3], off offset:32
	v_pk_mul_f32 v[10:11], v[40:41], v[8:9] op_sel_hi:[1,0]
	v_pk_mul_f32 v[16:17], v[38:39], v[8:9] op_sel_hi:[1,0]
	v_pk_mul_f32 v[2:3], v[228:229], v[10:11]
	v_pk_mul_f32 v[4:5], v[230:231], v[16:17]
	v_cvt_pk_bf16_f32 v2, v2, v3
	v_cvt_pk_bf16_f32 v3, v4, v5
	global_store_dwordx2 v[6:7], v[2:3], off offset:64
	v_pk_mul_f32 v[10:11], v[32:33], v[8:9] op_sel_hi:[1,0]
	v_pk_mul_f32 v[16:17], v[34:35], v[8:9] op_sel_hi:[1,0]
	v_pk_mul_f32 v[2:3], v[232:233], v[10:11]
	v_pk_mul_f32 v[4:5], v[234:235], v[16:17]
	v_cvt_pk_bf16_f32 v2, v2, v3
	v_cvt_pk_bf16_f32 v3, v4, v5
	global_store_dwordx2 v[6:7], v[2:3], off offset:96
	v_pk_mul_f32 v[10:11], v[28:29], v[8:9] op_sel_hi:[1,0]
	v_pk_mul_f32 v[16:17], v[30:31], v[8:9] op_sel_hi:[1,0]
	v_pk_mul_f32 v[2:3], v[10:11], v[236:237]
	v_pk_mul_f32 v[4:5], v[16:17], v[238:239]
	v_cvt_pk_bf16_f32 v2, v2, v3
	v_cvt_pk_bf16_f32 v3, v4, v5
	global_store_dwordx2 v[6:7], v[2:3], off offset:128
	v_pk_mul_f32 v[10:11], v[24:25], v[8:9] op_sel_hi:[1,0]
	v_pk_mul_f32 v[16:17], v[26:27], v[8:9] op_sel_hi:[1,0]
	v_pk_mul_f32 v[2:3], v[10:11], v[240:241]
	v_pk_mul_f32 v[4:5], v[16:17], v[242:243]
	v_cvt_pk_bf16_f32 v2, v2, v3
	v_cvt_pk_bf16_f32 v3, v4, v5
	global_store_dwordx2 v[6:7], v[2:3], off offset:160
	v_pk_mul_f32 v[10:11], v[20:21], v[8:9] op_sel_hi:[1,0]
	v_pk_mul_f32 v[16:17], v[22:23], v[8:9] op_sel_hi:[1,0]
	v_pk_mul_f32 v[2:3], v[10:11], v[244:245]
	v_pk_mul_f32 v[4:5], v[16:17], v[246:247]
	v_cvt_pk_bf16_f32 v2, v2, v3
	v_cvt_pk_bf16_f32 v3, v4, v5
	global_store_dwordx2 v[6:7], v[2:3], off offset:192
	v_pk_mul_f32 v[10:11], v[12:13], v[8:9] op_sel_hi:[1,0]
	v_pk_mul_f32 v[8:9], v[14:15], v[8:9] op_sel_hi:[1,0]
	v_pk_mul_f32 v[2:3], v[10:11], v[248:249]
	v_pk_mul_f32 v[4:5], v[8:9], v[250:251]
	v_cvt_pk_bf16_f32 v2, v2, v3
	v_cvt_pk_bf16_f32 v3, v4, v5
	global_store_dwordx2 v[6:7], v[2:3], off offset:224
	s_branch .LBB0_1077

.LBB0_1146:
	s_cmp_gt_u32 s81, 3
	s_cselect_b64 s[82:83], -1, 0
	s_mov_b64 s[44:45], -1
	s_and_b64 vcc, exec, s[82:83]
	s_cbranch_vccnz .LBB0_1148
	s_add_i32 s48, s89, 0xffffff81
	s_and_b64 s[44:45], s[4:5], exec
	s_cselect_b32 s44, s81, s48
	s_lshl_b32 s44, s44, 6
	s_or_b32 s80, s44, s87
	s_mov_b64 s[44:45], 0

.LBB0_1150:
	s_waitcnt vmcnt(7)
	v_cvt_f32_f16_e32 v2, v156
	v_cvt_f32_f16_e32 v0, v142
	v_cvt_f32_f16_sdwa v3, v156 dst_sel:DWORD dst_unused:UNUSED_PAD src0_sel:WORD_1
	v_and_b32_e32 v5, 0xffff0000, v138
	v_exp_f32_e32 v114, v2
	v_exp_f32_e64 v116, -v2
	v_sub_f32_e32 v2, v0, v2
	v_exp_f32_e32 v118, v2
	v_cvt_f32_f16_sdwa v2, v142 dst_sel:DWORD dst_unused:UNUSED_PAD src0_sel:WORD_1
	v_exp_f32_e32 v115, v3
	v_exp_f32_e64 v117, -v3
	v_lshlrev_b32_e32 v4, 16, v138
	v_sub_f32_e32 v3, v2, v3
	v_exp_f32_e32 v3, v3
	v_lshlrev_b32_e32 v14, 16, v8
	v_and_b32_e32 v15, 0xffff0000, v8
	v_pk_mul_f32 v[114:115], v[114:115], v[14:15]
	v_mul_f32_e32 v3, v3, v5
	v_cvt_pk_bf16_f32 v3, v3, s0
	v_mul_f32_e32 v14, v118, v4
	v_pk_mul_f32 v[116:117], v[116:117], v[4:5]
	v_cvt_f32_f16_e32 v4, v157
	ds_write_b16 v197, v3 offset:32896
	v_cvt_f32_f16_e32 v3, v143
	v_cvt_pk_bf16_f32 v14, v14, s0
	ds_write_b16 v197, v14 offset:32768
	v_exp_f32_e32 v14, v4
	v_exp_f32_e64 v118, -v4
	v_sub_f32_e32 v4, v3, v4
	v_cvt_f32_f16_sdwa v5, v157 dst_sel:DWORD dst_unused:UNUSED_PAD src0_sel:WORD_1
	v_exp_f32_e32 v122, v4
	v_cvt_f32_f16_sdwa v4, v143 dst_sel:DWORD dst_unused:UNUSED_PAD src0_sel:WORD_1
	v_lshlrev_b32_e32 v12, 16, v139
	v_exp_f32_e32 v15, v5
	v_exp_f32_e64 v119, -v5
	v_sub_f32_e32 v5, v4, v5
	v_exp_f32_e32 v5, v5
	v_and_b32_e32 v13, 0xffff0000, v139
	v_lshlrev_b32_e32 v112, 16, v9
	v_and_b32_e32 v113, 0xffff0000, v9
	v_pk_mul_f32 v[120:121], v[14:15], v[112:113]
	v_mul_f32_e32 v14, v122, v12
	v_mul_f32_e32 v5, v5, v13
	v_cvt_pk_bf16_f32 v14, v14, s0
	v_cvt_pk_bf16_f32 v5, v5, s0
	ds_write_b16 v198, v14 offset:32768
	v_pk_mul_f32 v[118:119], v[118:119], v[12:13]
	ds_write_b16 v199, v5 offset:32768
	s_waitcnt vmcnt(6)
	v_cvt_f32_f16_e32 v12, v158
	v_cvt_f32_f16_e32 v5, v144
	v_cvt_f32_f16_sdwa v13, v158 dst_sel:DWORD dst_unused:UNUSED_PAD src0_sel:WORD_1
	v_lshlrev_b32_e32 v14, 16, v140
	v_exp_f32_e32 v126, v12
	v_exp_f32_e64 v228, -v12
	v_sub_f32_e32 v12, v5, v12
	v_exp_f32_e32 v175, v12
	v_cvt_f32_f16_sdwa v12, v144 dst_sel:DWORD dst_unused:UNUSED_PAD src0_sel:WORD_1
	v_exp_f32_e32 v127, v13
	v_exp_f32_e64 v229, -v13
	v_and_b32_e32 v15, 0xffff0000, v140
	v_sub_f32_e32 v13, v12, v13
	v_exp_f32_e32 v13, v13
	v_lshlrev_b32_e32 v122, 16, v10
	v_and_b32_e32 v123, 0xffff0000, v10
	v_pk_mul_f32 v[122:123], v[126:127], v[122:123]
	v_mul_f32_e32 v126, v175, v14
	v_mul_f32_e32 v13, v13, v15
	v_cvt_pk_bf16_f32 v126, v126, s0
	v_cvt_pk_bf16_f32 v13, v13, s0
	ds_write_b16 v200, v126 offset:32768
	v_pk_mul_f32 v[126:127], v[228:229], v[14:15]
	v_cvt_f32_f16_e32 v14, v159
	ds_write_b16 v201, v13 offset:32768
	v_cvt_f32_f16_e32 v13, v145
	v_cvt_f32_f16_sdwa v15, v159 dst_sel:DWORD dst_unused:UNUSED_PAD src0_sel:WORD_1
	v_exp_f32_e32 v228, v14
	v_exp_f32_e64 v230, -v14
	v_sub_f32_e32 v14, v13, v14
	v_exp_f32_e32 v175, v14
	v_cvt_f32_f16_sdwa v14, v145 dst_sel:DWORD dst_unused:UNUSED_PAD src0_sel:WORD_1
	v_exp_f32_e32 v229, v15
	v_exp_f32_e64 v231, -v15
	v_lshlrev_b32_e32 v112, 16, v141
	v_sub_f32_e32 v15, v14, v15
	v_exp_f32_e32 v15, v15
	v_and_b32_e32 v113, 0xffff0000, v141
	v_lshlrev_b32_e32 v124, 16, v11
	v_and_b32_e32 v125, 0xffff0000, v11
	v_mul_f32_e32 v175, v175, v112
	v_mul_f32_e32 v15, v15, v113
	v_pk_mul_f32 v[124:125], v[228:229], v[124:125]
	v_cvt_pk_bf16_f32 v175, v175, s0
	v_cvt_pk_bf16_f32 v15, v15, s0
	ds_write_b16 v202, v175 offset:32768
	v_pk_mul_f32 v[228:229], v[230:231], v[112:113]
	ds_write_b16 v203, v15 offset:32768
	v_cvt_pk_bf16_f32 v112, v114, v115
	v_cvt_pk_bf16_f32 v115, v124, v125
	s_waitcnt vmcnt(3)
	v_cvt_f32_f16_e32 v15, v164
	v_cvt_f32_f16_sdwa v124, v164 dst_sel:DWORD dst_unused:UNUSED_PAD src0_sel:WORD_1
	v_cvt_pk_bf16_f32 v114, v122, v123
	v_cvt_f32_f16_e32 v123, v142
	v_cvt_pk_bf16_f32 v113, v120, v121
	v_exp_f32_e32 v120, v15
	v_exp_f32_e32 v121, v124
	v_cvt_f32_f16_sdwa v125, v142 dst_sel:DWORD dst_unused:UNUSED_PAD src0_sel:WORD_1
	v_cvt_pk_bf16_f32 v116, v116, v117
	v_cvt_pk_bf16_f32 v117, v118, v119
	v_exp_f32_e64 v122, -v15
	v_sub_f32_e32 v15, v123, v15
	v_cvt_pk_bf16_f32 v118, v126, v127
	v_cvt_pk_bf16_f32 v119, v228, v229
	ds_write_b128 v173, v[112:115]
	ds_write_b128 v173, v[116:119] offset:16384
	v_lshlrev_b32_e32 v116, 16, v6
	v_and_b32_e32 v117, 0xffff0000, v6
	v_exp_f32_e32 v15, v15
	v_pk_mul_f32 v[116:117], v[120:121], v[116:117]
	v_sub_f32_e32 v120, v125, v124
	v_exp_f32_e64 v123, -v124
	v_exp_f32_e32 v124, v120
	v_lshlrev_b32_e32 v112, 16, v160
	v_mul_f32_e32 v15, v15, v112
	v_and_b32_e32 v113, 0xffff0000, v160
	v_cvt_pk_bf16_f32 v15, v15, s0
	ds_write_b16 v204, v15 offset:32768
	v_mul_f32_e32 v15, v124, v113
	v_pk_mul_f32 v[120:121], v[122:123], v[112:113]
	v_cvt_pk_bf16_f32 v15, v15, s0
	v_cvt_f32_f16_e32 v123, v165
	v_cvt_f32_f16_e32 v124, v143
	ds_write_b16 v204, v15 offset:32896
	v_cvt_f32_f16_sdwa v15, v165 dst_sel:DWORD dst_unused:UNUSED_PAD src0_sel:WORD_1
	v_cvt_f32_f16_sdwa v125, v143 dst_sel:DWORD dst_unused:UNUSED_PAD src0_sel:WORD_1
	v_exp_f32_e32 v112, v123
	v_exp_f32_e64 v122, -v123
	v_sub_f32_e32 v123, v124, v123
	v_exp_f32_e32 v113, v15
	v_exp_f32_e32 v124, v123
	v_exp_f32_e64 v123, -v15
	v_sub_f32_e32 v15, v125, v15
	v_exp_f32_e32 v15, v15
	v_lshlrev_b32_e32 v114, 16, v161
	v_and_b32_e32 v115, 0xffff0000, v161
	v_lshlrev_b32_e32 v118, 16, v7
	v_and_b32_e32 v119, 0xffff0000, v7
	v_pk_mul_f32 v[118:119], v[112:113], v[118:119]
	v_mul_f32_e32 v112, v124, v114
	v_mul_f32_e32 v15, v15, v115
	v_cvt_pk_bf16_f32 v112, v112, s0
	v_cvt_pk_bf16_f32 v15, v15, s0
	ds_write_b16 v205, v112 offset:32768
	ds_write_b16 v206, v15 offset:32768
	s_waitcnt vmcnt(2)
	v_cvt_f32_f16_e32 v15, v166
	v_cvt_f32_f16_e32 v194, v144
	v_cvt_f32_f16_sdwa v175, v166 dst_sel:DWORD dst_unused:UNUSED_PAD src0_sel:WORD_1
	v_lshlrev_b32_e32 v112, 16, v162
	v_exp_f32_e32 v228, v15
	v_exp_f32_e64 v230, -v15
	v_sub_f32_e32 v15, v194, v15
	v_cvt_f32_f16_sdwa v194, v144 dst_sel:DWORD dst_unused:UNUSED_PAD src0_sel:WORD_1
	v_exp_f32_e32 v15, v15
	v_exp_f32_e32 v229, v175
	v_exp_f32_e64 v231, -v175
	v_sub_f32_e32 v175, v194, v175
	v_exp_f32_e32 v175, v175
	v_mul_f32_e32 v15, v15, v112
	v_and_b32_e32 v113, 0xffff0000, v162
	v_cvt_pk_bf16_f32 v15, v15, s0
	ds_write_b16 v207, v15 offset:32768
	v_mul_f32_e32 v15, v175, v113
	v_cvt_f32_f16_e32 v175, v167
	v_cvt_f32_f16_e32 v194, v145
	v_lshlrev_b32_e32 v124, 16, v170
	v_and_b32_e32 v125, 0xffff0000, v170
	v_cvt_pk_bf16_f32 v15, v15, s0
	v_pk_mul_f32 v[124:125], v[228:229], v[124:125]
	v_pk_mul_f32 v[228:229], v[230:231], v[112:113]
	ds_write_b16 v208, v15 offset:32768
	v_cvt_f32_f16_sdwa v15, v167 dst_sel:DWORD dst_unused:UNUSED_PAD src0_sel:WORD_1
	v_exp_f32_e32 v112, v175
	v_exp_f32_e64 v230, -v175
	v_sub_f32_e32 v175, v194, v175
	v_cvt_f32_f16_sdwa v194, v145 dst_sel:DWORD dst_unused:UNUSED_PAD src0_sel:WORD_1
	v_exp_f32_e32 v113, v15
	v_exp_f32_e32 v175, v175
	v_exp_f32_e64 v231, -v15
	v_sub_f32_e32 v15, v194, v15
	v_exp_f32_e32 v15, v15
	v_pk_mul_f32 v[122:123], v[122:123], v[114:115]
	v_lshlrev_b32_e32 v114, 16, v163
	v_lshlrev_b32_e32 v126, 16, v171
	v_and_b32_e32 v127, 0xffff0000, v171
	v_and_b32_e32 v115, 0xffff0000, v163
	v_pk_mul_f32 v[126:127], v[112:113], v[126:127]
	v_mul_f32_e32 v112, v175, v114
	v_cvt_pk_bf16_f32 v112, v112, s0
	v_mul_f32_e32 v15, v15, v115
	ds_write_b16 v209, v112 offset:32768
	v_pk_mul_f32 v[230:231], v[230:231], v[114:115]
	v_cvt_pk_bf16_f32 v15, v15, s0
	v_cvt_pk_bf16_f32 v112, v116, v117
	v_cvt_pk_bf16_f32 v113, v118, v119
	v_cvt_pk_bf16_f32 v114, v124, v125
	v_cvt_pk_bf16_f32 v115, v126, v127
	ds_write_b16 v210, v15 offset:32768
	v_cvt_pk_bf16_f32 v116, v120, v121
	v_cvt_pk_bf16_f32 v117, v122, v123
	v_cvt_pk_bf16_f32 v118, v228, v229
	v_cvt_pk_bf16_f32 v119, v230, v231
	ds_write_b128 v174, v[112:115]
	ds_write_b128 v174, v[116:119] offset:16384
	s_waitcnt vmcnt(1)
	ds_write_b128 v211, v[128:131] offset:49152
	s_waitcnt vmcnt(0)
	ds_write_b128 v211, v[132:135] offset:57344
	s_and_saveexec_b64 s[44:45], s[6:7]
	s_cbranch_execz .LBB0_1152
	v_exp_f32_e32 v112, v0
	v_exp_f32_e32 v113, v2
	v_exp_f32_e32 v114, v3
	v_exp_f32_e32 v115, v4
	v_exp_f32_e32 v2, v5
	v_exp_f32_e32 v3, v12
	v_exp_f32_e32 v4, v13
	v_exp_f32_e32 v5, v14
	ds_write_b128 v176, v[112:115]
	ds_write_b128 v176, v[2:5] offset:32

.LBB0_1227:
	s_or_b64 exec, exec, s[14:15]
	s_add_i32 s28, s28, s50
	s_add_i32 s27, s27, s50
	s_lshl_b32 s11, s10, 12
	s_lshl_b32 s13, s12, 1
	s_add_u32 s11, s11, s13
	s_add_u32 s16, s52, s11
	s_addc_u32 s17, s53, 0
	s_lshl_b32 s11, s10, 11
	s_add_u32 s11, s11, s13
	s_add_u32 s30, s54, 0x2ce00000
	s_addc_u32 s31, s55, 0
	s_add_u32 s30, s30, s11
	s_addc_u32 s31, s31, 0
	v_and_b32_e32 v230, 63, v148
	v_lshrrev_b32_e32 v231, 6, v148
	v_lshrrev_b32_e32 v232, 2, v231
	v_and_b32_e32 v231, 3, v231
	v_and_b32_e32 v233, 15, v230
	v_lshrrev_b32_e32 v230, 4, v230
	v_lshl_add_u32 v232, v232, 6, v233
	v_mul_u32_u24_e32 v226, 0x110, v232
	v_lshlrev_b32_e32 v234, 6, v231
	v_lshl_add_u32 v234, v230, 3, v234
	v_add_u32_e32 v226, v226, v234
	v_add_u32_e32 v246, 0x11000, v226
	v_lshrrev_b32_e32 v230, 4, v148
	v_and_b32_e32 v231, 15, v148
	v_mul_u32_u24_e32 v227, 0x110, v230
	v_lshl_add_u32 v227, v231, 4, v227
	v_add_u32_e32 v247, 0x11000, v227
	v_lshlrev_b32_e32 v228, 11, v230
	v_lshl_add_u32 v228, v231, 4, v228
	v_lshlrev_b32_e32 v229, 12, v230
	v_lshl_add_u32 v229, v231, 4, v229
	s_mov_b32 s18, s16
	s_mov_b32 s19, s17
	global_load_dwordx4 v[162:165], v229, s[18:19]
	global_load_dwordx4 v[166:169], v229, s[18:19] offset:2048
	s_add_u32 s18, s16, 0x20000
	s_addc_u32 s19, s17, 0
	global_load_dwordx4 v[170:173], v229, s[18:19]
	global_load_dwordx4 v[174:177], v229, s[18:19] offset:2048
	s_add_u32 s18, s16, 0x40000
	s_addc_u32 s19, s17, 0
	global_load_dwordx4 v[178:181], v229, s[18:19]
	global_load_dwordx4 v[182:185], v229, s[18:19] offset:2048
	s_add_u32 s18, s16, 0x60000
	s_addc_u32 s19, s17, 0
	global_load_dwordx4 v[186:189], v229, s[18:19]
	global_load_dwordx4 v[190:193], v229, s[18:19] offset:2048
	s_add_u32 s18, s16, 0x100
	s_addc_u32 s19, s17, 0
	global_load_dwordx4 v[194:197], v229, s[18:19]
	global_load_dwordx4 v[198:201], v229, s[18:19] offset:2048
	s_add_u32 s18, s16, 0x20100
	s_addc_u32 s19, s17, 0
	global_load_dwordx4 v[202:205], v229, s[18:19]
	global_load_dwordx4 v[206:209], v229, s[18:19] offset:2048
	s_add_u32 s18, s16, 0x40100
	s_addc_u32 s19, s17, 0
	global_load_dwordx4 v[210:213], v229, s[18:19]
	global_load_dwordx4 v[214:217], v229, s[18:19] offset:2048
	s_add_u32 s18, s16, 0x60100
	s_addc_u32 s19, s17, 0
	global_load_dwordx4 v[218:221], v229, s[18:19]
	global_load_dwordx4 v[222:225], v229, s[18:19] offset:2048
	s_waitcnt vmcnt(8)
	ds_write_b128 v227, v[162:165] offset:0
	ds_write_b128 v227, v[166:169] offset:34816
	ds_write_b128 v227, v[170:173] offset:8704
	ds_write_b128 v227, v[174:177] offset:43520
	ds_write_b128 v227, v[178:181] offset:17408
	ds_write_b128 v227, v[182:185] offset:52224
	ds_write_b128 v227, v[186:189] offset:26112
	ds_write_b128 v227, v[190:193] offset:60928
	s_waitcnt lgkmcnt(0)
	s_barrier
	ds_read_b64 v[162:163], v226 offset:0
	ds_read_b64 v[164:165], v226 offset:34816
	ds_read_b64 v[166:167], v226 offset:32
	ds_read_b64 v[168:169], v226 offset:34848
	ds_read_b64 v[170:171], v226 offset:4352
	ds_read_b64 v[172:173], v226 offset:39168
	ds_read_b64 v[174:175], v226 offset:4384
	ds_read_b64 v[176:177], v226 offset:39200
	ds_read_b64 v[178:179], v226 offset:8704
	ds_read_b64 v[180:181], v226 offset:43520
	ds_read_b64 v[182:183], v226 offset:8736
	ds_read_b64 v[184:185], v226 offset:43552
	ds_read_b64 v[186:187], v226 offset:13056
	ds_read_b64 v[188:189], v226 offset:47872
	ds_read_b64 v[190:191], v226 offset:13088
	ds_read_b64 v[192:193], v226 offset:47904
	s_waitcnt lgkmcnt(14)
	v_lshlrev_b32_e32 v230, 16, v162
	v_and_b32_e32 v231, 0xffff0000, v162
	v_lshlrev_b32_e32 v232, 16, v163
	v_and_b32_e32 v233, 0xffff0000, v163
	v_lshlrev_b32_e32 v234, 16, v164
	v_and_b32_e32 v235, 0xffff0000, v164
	v_lshlrev_b32_e32 v236, 16, v165
	v_and_b32_e32 v237, 0xffff0000, v165
	v_fma_f32 v238, v120, v234, v230
	v_fma_f32 v239, v121, v235, v231
	v_fma_f32 v240, v122, v236, v232
	v_fma_f32 v241, v123, v237, v233
	v_cvt_pk_bf16_f32 v242, v238, v239
	v_cvt_pk_bf16_f32 v243, v240, v241
	ds_write_b64 v246, v[242:243] offset:0
	s_waitcnt lgkmcnt(12)
	v_lshlrev_b32_e32 v230, 16, v166
	v_and_b32_e32 v231, 0xffff0000, v166
	v_lshlrev_b32_e32 v232, 16, v167
	v_and_b32_e32 v233, 0xffff0000, v167
	v_lshlrev_b32_e32 v234, 16, v168
	v_and_b32_e32 v235, 0xffff0000, v168
	v_lshlrev_b32_e32 v236, 16, v169
	v_and_b32_e32 v237, 0xffff0000, v169
	v_fma_f32 v238, v124, v234, v230
	v_fma_f32 v239, v125, v235, v231
	v_fma_f32 v240, v126, v236, v232
	v_fma_f32 v241, v127, v237, v233
	v_cvt_pk_bf16_f32 v244, v238, v239
	v_cvt_pk_bf16_f32 v245, v240, v241
	ds_write_b64 v246, v[244:245] offset:32
	s_waitcnt lgkmcnt(10)
	v_lshlrev_b32_e32 v230, 16, v170
	v_and_b32_e32 v231, 0xffff0000, v170
	v_lshlrev_b32_e32 v232, 16, v171
	v_and_b32_e32 v233, 0xffff0000, v171
	v_lshlrev_b32_e32 v234, 16, v172
	v_and_b32_e32 v235, 0xffff0000, v172
	v_lshlrev_b32_e32 v236, 16, v173
	v_and_b32_e32 v237, 0xffff0000, v173
	v_fma_f32 v238, v112, v234, v230
	v_fma_f32 v239, v113, v235, v231
	v_fma_f32 v240, v114, v236, v232
	v_fma_f32 v241, v115, v237, v233
	v_cvt_pk_bf16_f32 v242, v238, v239
	v_cvt_pk_bf16_f32 v243, v240, v241
	ds_write_b64 v246, v[242:243] offset:4352
	s_waitcnt lgkmcnt(8)
	v_lshlrev_b32_e32 v230, 16, v174
	v_and_b32_e32 v231, 0xffff0000, v174
	v_lshlrev_b32_e32 v232, 16, v175
	v_and_b32_e32 v233, 0xffff0000, v175
	v_lshlrev_b32_e32 v234, 16, v176
	v_and_b32_e32 v235, 0xffff0000, v176
	v_lshlrev_b32_e32 v236, 16, v177
	v_and_b32_e32 v237, 0xffff0000, v177
	v_fma_f32 v238, v116, v234, v230
	v_fma_f32 v239, v117, v235, v231
	v_fma_f32 v240, v118, v236, v232
	v_fma_f32 v241, v119, v237, v233
	v_cvt_pk_bf16_f32 v244, v238, v239
	v_cvt_pk_bf16_f32 v245, v240, v241
	ds_write_b64 v246, v[244:245] offset:4384
	s_waitcnt lgkmcnt(6)
	v_lshlrev_b32_e32 v230, 16, v178
	v_and_b32_e32 v231, 0xffff0000, v178
	v_lshlrev_b32_e32 v232, 16, v179
	v_and_b32_e32 v233, 0xffff0000, v179
	v_lshlrev_b32_e32 v234, 16, v180
	v_and_b32_e32 v235, 0xffff0000, v180
	v_lshlrev_b32_e32 v236, 16, v181
	v_and_b32_e32 v237, 0xffff0000, v181
	v_fma_f32 v238, v96, v234, v230
	v_fma_f32 v239, v97, v235, v231
	v_fma_f32 v240, v98, v236, v232
	v_fma_f32 v241, v99, v237, v233
	v_cvt_pk_bf16_f32 v242, v238, v239
	v_cvt_pk_bf16_f32 v243, v240, v241
	ds_write_b64 v246, v[242:243] offset:8704
	s_waitcnt lgkmcnt(4)
	v_lshlrev_b32_e32 v230, 16, v182
	v_and_b32_e32 v231, 0xffff0000, v182
	v_lshlrev_b32_e32 v232, 16, v183
	v_and_b32_e32 v233, 0xffff0000, v183
	v_lshlrev_b32_e32 v234, 16, v184
	v_and_b32_e32 v235, 0xffff0000, v184
	v_lshlrev_b32_e32 v236, 16, v185
	v_and_b32_e32 v237, 0xffff0000, v185
	v_fma_f32 v238, v100, v234, v230
	v_fma_f32 v239, v101, v235, v231
	v_fma_f32 v240, v102, v236, v232
	v_fma_f32 v241, v103, v237, v233
	v_cvt_pk_bf16_f32 v244, v238, v239
	v_cvt_pk_bf16_f32 v245, v240, v241
	ds_write_b64 v246, v[244:245] offset:8736
	s_waitcnt lgkmcnt(2)
	v_lshlrev_b32_e32 v230, 16, v186
	v_and_b32_e32 v231, 0xffff0000, v186
	v_lshlrev_b32_e32 v232, 16, v187
	v_and_b32_e32 v233, 0xffff0000, v187
	v_lshlrev_b32_e32 v234, 16, v188
	v_and_b32_e32 v235, 0xffff0000, v188
	v_lshlrev_b32_e32 v236, 16, v189
	v_and_b32_e32 v237, 0xffff0000, v189
	v_fma_f32 v238, v104, v234, v230
	v_fma_f32 v239, v105, v235, v231
	v_fma_f32 v240, v106, v236, v232
	v_fma_f32 v241, v107, v237, v233
	v_cvt_pk_bf16_f32 v242, v238, v239
	v_cvt_pk_bf16_f32 v243, v240, v241
	ds_write_b64 v246, v[242:243] offset:13056
	s_waitcnt lgkmcnt(0)
	v_lshlrev_b32_e32 v230, 16, v190
	v_and_b32_e32 v231, 0xffff0000, v190
	v_lshlrev_b32_e32 v232, 16, v191
	v_and_b32_e32 v233, 0xffff0000, v191
	v_lshlrev_b32_e32 v234, 16, v192
	v_and_b32_e32 v235, 0xffff0000, v192
	v_lshlrev_b32_e32 v236, 16, v193
	v_and_b32_e32 v237, 0xffff0000, v193
	v_fma_f32 v238, v108, v234, v230
	v_fma_f32 v239, v109, v235, v231
	v_fma_f32 v240, v110, v236, v232
	v_fma_f32 v241, v111, v237, v233
	v_cvt_pk_bf16_f32 v244, v238, v239
	v_cvt_pk_bf16_f32 v245, v240, v241
	ds_write_b64 v246, v[244:245] offset:13088
	s_waitcnt lgkmcnt(0)
	s_barrier
	ds_read_b128 v[230:233], v247 offset:0
	ds_read_b128 v[234:237], v247 offset:8704
	s_mov_b32 s18, s30
	s_mov_b32 s19, s31
	s_waitcnt lgkmcnt(1)
	global_store_dwordx4 v228, v[230:233], s[18:19] sc1
	s_add_u32 s18, s30, 0x10000
	s_addc_u32 s19, s31, 0
	s_waitcnt lgkmcnt(0)
	global_store_dwordx4 v228, v[234:237], s[18:19] sc1
	ds_read_b128 v[230:233], v247 offset:17408
	ds_read_b128 v[234:237], v247 offset:26112
	s_add_u32 s18, s30, 0x20000
	s_addc_u32 s19, s31, 0
	s_waitcnt lgkmcnt(1)
	global_store_dwordx4 v228, v[230:233], s[18:19] sc1
	s_add_u32 s18, s30, 0x30000
	s_addc_u32 s19, s31, 0
	s_waitcnt lgkmcnt(0)
	global_store_dwordx4 v228, v[234:237], s[18:19] sc1
	s_add_u32 s18, s16, 0x80000
	s_addc_u32 s19, s17, 0
	global_load_dwordx4 v[162:165], v229, s[18:19]
	global_load_dwordx4 v[166:169], v229, s[18:19] offset:2048
	s_add_u32 s18, s16, 0xa0000
	s_addc_u32 s19, s17, 0
	global_load_dwordx4 v[170:173], v229, s[18:19]
	global_load_dwordx4 v[174:177], v229, s[18:19] offset:2048
	s_add_u32 s18, s16, 0xc0000
	s_addc_u32 s19, s17, 0
	global_load_dwordx4 v[178:181], v229, s[18:19]
	global_load_dwordx4 v[182:185], v229, s[18:19] offset:2048
	s_add_u32 s18, s16, 0xe0000
	s_addc_u32 s19, s17, 0
	global_load_dwordx4 v[186:189], v229, s[18:19]
	global_load_dwordx4 v[190:193], v229, s[18:19] offset:2048
	s_waitcnt vmcnt(8)
	ds_write_b128 v227, v[194:197] offset:0
	ds_write_b128 v227, v[198:201] offset:34816
	ds_write_b128 v227, v[202:205] offset:8704
	ds_write_b128 v227, v[206:209] offset:43520
	ds_write_b128 v227, v[210:213] offset:17408
	ds_write_b128 v227, v[214:217] offset:52224
	ds_write_b128 v227, v[218:221] offset:26112
	ds_write_b128 v227, v[222:225] offset:60928
	s_waitcnt lgkmcnt(0)
	s_barrier
	ds_read_b64 v[194:195], v226 offset:0
	ds_read_b64 v[196:197], v226 offset:34816
	ds_read_b64 v[198:199], v226 offset:32
	ds_read_b64 v[200:201], v226 offset:34848
	ds_read_b64 v[202:203], v226 offset:4352
	ds_read_b64 v[204:205], v226 offset:39168
	ds_read_b64 v[206:207], v226 offset:4384
	ds_read_b64 v[208:209], v226 offset:39200
	ds_read_b64 v[210:211], v226 offset:8704
	ds_read_b64 v[212:213], v226 offset:43520
	ds_read_b64 v[214:215], v226 offset:8736
	ds_read_b64 v[216:217], v226 offset:43552
	ds_read_b64 v[218:219], v226 offset:13056
	ds_read_b64 v[220:221], v226 offset:47872
	ds_read_b64 v[222:223], v226 offset:13088
	ds_read_b64 v[224:225], v226 offset:47904
	s_waitcnt lgkmcnt(14)
	v_lshlrev_b32_e32 v230, 16, v194
	v_and_b32_e32 v231, 0xffff0000, v194
	v_lshlrev_b32_e32 v232, 16, v195
	v_and_b32_e32 v233, 0xffff0000, v195
	v_lshlrev_b32_e32 v234, 16, v196
	v_and_b32_e32 v235, 0xffff0000, v196
	v_lshlrev_b32_e32 v236, 16, v197
	v_and_b32_e32 v237, 0xffff0000, v197
	v_fma_f32 v238, v84, v234, v230
	v_fma_f32 v239, v85, v235, v231
	v_fma_f32 v240, v86, v236, v232
	v_fma_f32 v241, v87, v237, v233
	v_cvt_pk_bf16_f32 v242, v238, v239
	v_cvt_pk_bf16_f32 v243, v240, v241
	ds_write_b64 v246, v[242:243] offset:0
	s_waitcnt lgkmcnt(12)
	v_lshlrev_b32_e32 v230, 16, v198
	v_and_b32_e32 v231, 0xffff0000, v198
	v_lshlrev_b32_e32 v232, 16, v199
	v_and_b32_e32 v233, 0xffff0000, v199
	v_lshlrev_b32_e32 v234, 16, v200
	v_and_b32_e32 v235, 0xffff0000, v200
	v_lshlrev_b32_e32 v236, 16, v201
	v_and_b32_e32 v237, 0xffff0000, v201
	v_fma_f32 v238, v88, v234, v230
	v_fma_f32 v239, v89, v235, v231
	v_fma_f32 v240, v90, v236, v232
	v_fma_f32 v241, v91, v237, v233
	v_cvt_pk_bf16_f32 v244, v238, v239
	v_cvt_pk_bf16_f32 v245, v240, v241
	ds_write_b64 v246, v[244:245] offset:32
	s_waitcnt lgkmcnt(10)
	v_lshlrev_b32_e32 v230, 16, v202
	v_and_b32_e32 v231, 0xffff0000, v202
	v_lshlrev_b32_e32 v232, 16, v203
	v_and_b32_e32 v233, 0xffff0000, v203
	v_lshlrev_b32_e32 v234, 16, v204
	v_and_b32_e32 v235, 0xffff0000, v204
	v_lshlrev_b32_e32 v236, 16, v205
	v_and_b32_e32 v237, 0xffff0000, v205
	v_fma_f32 v238, v92, v234, v230
	v_fma_f32 v239, v93, v235, v231
	v_fma_f32 v240, v94, v236, v232
	v_fma_f32 v241, v95, v237, v233
	v_cvt_pk_bf16_f32 v242, v238, v239
	v_cvt_pk_bf16_f32 v243, v240, v241
	ds_write_b64 v246, v[242:243] offset:4352
	s_waitcnt lgkmcnt(8)
	v_lshlrev_b32_e32 v230, 16, v206
	v_and_b32_e32 v231, 0xffff0000, v206
	v_lshlrev_b32_e32 v232, 16, v207
	v_and_b32_e32 v233, 0xffff0000, v207
	v_lshlrev_b32_e32 v234, 16, v208
	v_and_b32_e32 v235, 0xffff0000, v208
	v_lshlrev_b32_e32 v236, 16, v209
	v_and_b32_e32 v237, 0xffff0000, v209
	v_fma_f32 v238, v80, v234, v230
	v_fma_f32 v239, v81, v235, v231
	v_fma_f32 v240, v82, v236, v232
	v_fma_f32 v241, v83, v237, v233
	v_cvt_pk_bf16_f32 v244, v238, v239
	v_cvt_pk_bf16_f32 v245, v240, v241
	ds_write_b64 v246, v[244:245] offset:4384
	s_waitcnt lgkmcnt(6)
	v_lshlrev_b32_e32 v230, 16, v210
	v_and_b32_e32 v231, 0xffff0000, v210
	v_lshlrev_b32_e32 v232, 16, v211
	v_and_b32_e32 v233, 0xffff0000, v211
	v_lshlrev_b32_e32 v234, 16, v212
	v_and_b32_e32 v235, 0xffff0000, v212
	v_lshlrev_b32_e32 v236, 16, v213
	v_and_b32_e32 v237, 0xffff0000, v213
	v_fma_f32 v238, v64, v234, v230
	v_fma_f32 v239, v65, v235, v231
	v_fma_f32 v240, v66, v236, v232
	v_fma_f32 v241, v67, v237, v233
	v_cvt_pk_bf16_f32 v242, v238, v239
	v_cvt_pk_bf16_f32 v243, v240, v241
	ds_write_b64 v246, v[242:243] offset:8704
	s_waitcnt lgkmcnt(4)
	v_lshlrev_b32_e32 v230, 16, v214
	v_and_b32_e32 v231, 0xffff0000, v214
	v_lshlrev_b32_e32 v232, 16, v215
	v_and_b32_e32 v233, 0xffff0000, v215
	v_lshlrev_b32_e32 v234, 16, v216
	v_and_b32_e32 v235, 0xffff0000, v216
	v_lshlrev_b32_e32 v236, 16, v217
	v_and_b32_e32 v237, 0xffff0000, v217
	v_fma_f32 v238, v68, v234, v230
	v_fma_f32 v239, v69, v235, v231
	v_fma_f32 v240, v70, v236, v232
	v_fma_f32 v241, v71, v237, v233
	v_cvt_pk_bf16_f32 v244, v238, v239
	v_cvt_pk_bf16_f32 v245, v240, v241
	ds_write_b64 v246, v[244:245] offset:8736
	s_waitcnt lgkmcnt(2)
	v_lshlrev_b32_e32 v230, 16, v218
	v_and_b32_e32 v231, 0xffff0000, v218
	v_lshlrev_b32_e32 v232, 16, v219
	v_and_b32_e32 v233, 0xffff0000, v219
	v_lshlrev_b32_e32 v234, 16, v220
	v_and_b32_e32 v235, 0xffff0000, v220
	v_lshlrev_b32_e32 v236, 16, v221
	v_and_b32_e32 v237, 0xffff0000, v221
	v_fma_f32 v238, v72, v234, v230
	v_fma_f32 v239, v73, v235, v231
	v_fma_f32 v240, v74, v236, v232
	v_fma_f32 v241, v75, v237, v233
	v_cvt_pk_bf16_f32 v242, v238, v239
	v_cvt_pk_bf16_f32 v243, v240, v241
	ds_write_b64 v246, v[242:243] offset:13056
	s_waitcnt lgkmcnt(0)
	v_lshlrev_b32_e32 v230, 16, v222
	v_and_b32_e32 v231, 0xffff0000, v222
	v_lshlrev_b32_e32 v232, 16, v223
	v_and_b32_e32 v233, 0xffff0000, v223
	v_lshlrev_b32_e32 v234, 16, v224
	v_and_b32_e32 v235, 0xffff0000, v224
	v_lshlrev_b32_e32 v236, 16, v225
	v_and_b32_e32 v237, 0xffff0000, v225
	v_fma_f32 v238, v76, v234, v230
	v_fma_f32 v239, v77, v235, v231
	v_fma_f32 v240, v78, v236, v232
	v_fma_f32 v241, v79, v237, v233
	v_cvt_pk_bf16_f32 v244, v238, v239
	v_cvt_pk_bf16_f32 v245, v240, v241
	ds_write_b64 v246, v[244:245] offset:13088
	s_waitcnt lgkmcnt(0)
	s_barrier
	ds_read_b128 v[230:233], v247 offset:0
	ds_read_b128 v[234:237], v247 offset:8704
	s_add_u32 s18, s30, 0x100
	s_addc_u32 s19, s31, 0
	s_waitcnt lgkmcnt(1)
	global_store_dwordx4 v228, v[230:233], s[18:19] sc1
	s_add_u32 s18, s30, 0x10100
	s_addc_u32 s19, s31, 0
	s_waitcnt lgkmcnt(0)
	global_store_dwordx4 v228, v[234:237], s[18:19] sc1
	ds_read_b128 v[230:233], v247 offset:17408
	ds_read_b128 v[234:237], v247 offset:26112
	s_add_u32 s18, s30, 0x20100
	s_addc_u32 s19, s31, 0
	s_waitcnt lgkmcnt(1)
	global_store_dwordx4 v228, v[230:233], s[18:19] sc1
	s_add_u32 s18, s30, 0x30100
	s_addc_u32 s19, s31, 0
	s_waitcnt lgkmcnt(0)
	global_store_dwordx4 v228, v[234:237], s[18:19] sc1
	s_add_u32 s18, s16, 0x80100
	s_addc_u32 s19, s17, 0
	global_load_dwordx4 v[194:197], v229, s[18:19]
	global_load_dwordx4 v[198:201], v229, s[18:19] offset:2048
	s_add_u32 s18, s16, 0xa0100
	s_addc_u32 s19, s17, 0
	global_load_dwordx4 v[202:205], v229, s[18:19]
	global_load_dwordx4 v[206:209], v229, s[18:19] offset:2048
	s_add_u32 s18, s16, 0xc0100
	s_addc_u32 s19, s17, 0
	global_load_dwordx4 v[210:213], v229, s[18:19]
	global_load_dwordx4 v[214:217], v229, s[18:19] offset:2048
	s_add_u32 s18, s16, 0xe0100
	s_addc_u32 s19, s17, 0
	global_load_dwordx4 v[218:221], v229, s[18:19]
	global_load_dwordx4 v[222:225], v229, s[18:19] offset:2048
	s_waitcnt vmcnt(8)
	ds_write_b128 v227, v[162:165] offset:0
	ds_write_b128 v227, v[166:169] offset:34816
	ds_write_b128 v227, v[170:173] offset:8704
	ds_write_b128 v227, v[174:177] offset:43520
	ds_write_b128 v227, v[178:181] offset:17408
	ds_write_b128 v227, v[182:185] offset:52224
	ds_write_b128 v227, v[186:189] offset:26112
	ds_write_b128 v227, v[190:193] offset:60928
	s_waitcnt lgkmcnt(0)
	s_barrier
	ds_read_b64 v[162:163], v226 offset:0
	ds_read_b64 v[164:165], v226 offset:34816
	ds_read_b64 v[166:167], v226 offset:32
	ds_read_b64 v[168:169], v226 offset:34848
	ds_read_b64 v[170:171], v226 offset:4352
	ds_read_b64 v[172:173], v226 offset:39168
	ds_read_b64 v[174:175], v226 offset:4384
	ds_read_b64 v[176:177], v226 offset:39200
	ds_read_b64 v[178:179], v226 offset:8704
	ds_read_b64 v[180:181], v226 offset:43520
	ds_read_b64 v[182:183], v226 offset:8736
	ds_read_b64 v[184:185], v226 offset:43552
	ds_read_b64 v[186:187], v226 offset:13056
	ds_read_b64 v[188:189], v226 offset:47872
	ds_read_b64 v[190:191], v226 offset:13088
	ds_read_b64 v[192:193], v226 offset:47904
	s_waitcnt lgkmcnt(14)
	v_lshlrev_b32_e32 v230, 16, v162
	v_and_b32_e32 v231, 0xffff0000, v162
	v_lshlrev_b32_e32 v232, 16, v163
	v_and_b32_e32 v233, 0xffff0000, v163
	v_lshlrev_b32_e32 v234, 16, v164
	v_and_b32_e32 v235, 0xffff0000, v164
	v_lshlrev_b32_e32 v236, 16, v165
	v_and_b32_e32 v237, 0xffff0000, v165
	v_fma_f32 v238, v48, v234, v230
	v_fma_f32 v239, v49, v235, v231
	v_fma_f32 v240, v50, v236, v232
	v_fma_f32 v241, v51, v237, v233
	v_cvt_pk_bf16_f32 v242, v238, v239
	v_cvt_pk_bf16_f32 v243, v240, v241
	ds_write_b64 v246, v[242:243] offset:0
	s_waitcnt lgkmcnt(12)
	v_lshlrev_b32_e32 v230, 16, v166
	v_and_b32_e32 v231, 0xffff0000, v166
	v_lshlrev_b32_e32 v232, 16, v167
	v_and_b32_e32 v233, 0xffff0000, v167
	v_lshlrev_b32_e32 v234, 16, v168
	v_and_b32_e32 v235, 0xffff0000, v168
	v_lshlrev_b32_e32 v236, 16, v169
	v_and_b32_e32 v237, 0xffff0000, v169
	v_fma_f32 v238, v52, v234, v230
	v_fma_f32 v239, v53, v235, v231
	v_fma_f32 v240, v54, v236, v232
	v_fma_f32 v241, v55, v237, v233
	v_cvt_pk_bf16_f32 v244, v238, v239
	v_cvt_pk_bf16_f32 v245, v240, v241
	ds_write_b64 v246, v[244:245] offset:32
	s_waitcnt lgkmcnt(10)
	v_lshlrev_b32_e32 v230, 16, v170
	v_and_b32_e32 v231, 0xffff0000, v170
	v_lshlrev_b32_e32 v232, 16, v171
	v_and_b32_e32 v233, 0xffff0000, v171
	v_lshlrev_b32_e32 v234, 16, v172
	v_and_b32_e32 v235, 0xffff0000, v172
	v_lshlrev_b32_e32 v236, 16, v173
	v_and_b32_e32 v237, 0xffff0000, v173
	v_fma_f32 v238, v56, v234, v230
	v_fma_f32 v239, v57, v235, v231
	v_fma_f32 v240, v58, v236, v232
	v_fma_f32 v241, v59, v237, v233
	v_cvt_pk_bf16_f32 v242, v238, v239
	v_cvt_pk_bf16_f32 v243, v240, v241
	ds_write_b64 v246, v[242:243] offset:4352
	s_waitcnt lgkmcnt(8)
	v_lshlrev_b32_e32 v230, 16, v174
	v_and_b32_e32 v231, 0xffff0000, v174
	v_lshlrev_b32_e32 v232, 16, v175
	v_and_b32_e32 v233, 0xffff0000, v175
	v_lshlrev_b32_e32 v234, 16, v176
	v_and_b32_e32 v235, 0xffff0000, v176
	v_lshlrev_b32_e32 v236, 16, v177
	v_and_b32_e32 v237, 0xffff0000, v177
	v_fma_f32 v238, v60, v234, v230
	v_fma_f32 v239, v61, v235, v231
	v_fma_f32 v240, v62, v236, v232
	v_fma_f32 v241, v63, v237, v233
	v_cvt_pk_bf16_f32 v244, v238, v239
	v_cvt_pk_bf16_f32 v245, v240, v241
	ds_write_b64 v246, v[244:245] offset:4384
	s_waitcnt lgkmcnt(6)
	v_lshlrev_b32_e32 v230, 16, v178
	v_and_b32_e32 v231, 0xffff0000, v178
	v_lshlrev_b32_e32 v232, 16, v179
	v_and_b32_e32 v233, 0xffff0000, v179
	v_lshlrev_b32_e32 v234, 16, v180
	v_and_b32_e32 v235, 0xffff0000, v180
	v_lshlrev_b32_e32 v236, 16, v181
	v_and_b32_e32 v237, 0xffff0000, v181
	v_fma_f32 v238, v32, v234, v230
	v_fma_f32 v239, v33, v235, v231
	v_fma_f32 v240, v34, v236, v232
	v_fma_f32 v241, v35, v237, v233
	v_cvt_pk_bf16_f32 v242, v238, v239
	v_cvt_pk_bf16_f32 v243, v240, v241
	ds_write_b64 v246, v[242:243] offset:8704
	s_waitcnt lgkmcnt(4)
	v_lshlrev_b32_e32 v230, 16, v182
	v_and_b32_e32 v231, 0xffff0000, v182
	v_lshlrev_b32_e32 v232, 16, v183
	v_and_b32_e32 v233, 0xffff0000, v183
	v_lshlrev_b32_e32 v234, 16, v184
	v_and_b32_e32 v235, 0xffff0000, v184
	v_lshlrev_b32_e32 v236, 16, v185
	v_and_b32_e32 v237, 0xffff0000, v185
	v_fma_f32 v238, v36, v234, v230
	v_fma_f32 v239, v37, v235, v231
	v_fma_f32 v240, v38, v236, v232
	v_fma_f32 v241, v39, v237, v233
	v_cvt_pk_bf16_f32 v244, v238, v239
	v_cvt_pk_bf16_f32 v245, v240, v241
	ds_write_b64 v246, v[244:245] offset:8736
	s_waitcnt lgkmcnt(2)
	v_lshlrev_b32_e32 v230, 16, v186
	v_and_b32_e32 v231, 0xffff0000, v186
	v_lshlrev_b32_e32 v232, 16, v187
	v_and_b32_e32 v233, 0xffff0000, v187
	v_lshlrev_b32_e32 v234, 16, v188
	v_and_b32_e32 v235, 0xffff0000, v188
	v_lshlrev_b32_e32 v236, 16, v189
	v_and_b32_e32 v237, 0xffff0000, v189
	v_fma_f32 v238, v40, v234, v230
	v_fma_f32 v239, v41, v235, v231
	v_fma_f32 v240, v42, v236, v232
	v_fma_f32 v241, v43, v237, v233
	v_cvt_pk_bf16_f32 v242, v238, v239
	v_cvt_pk_bf16_f32 v243, v240, v241
	ds_write_b64 v246, v[242:243] offset:13056
	s_waitcnt lgkmcnt(0)
	v_lshlrev_b32_e32 v230, 16, v190
	v_and_b32_e32 v231, 0xffff0000, v190
	v_lshlrev_b32_e32 v232, 16, v191
	v_and_b32_e32 v233, 0xffff0000, v191
	v_lshlrev_b32_e32 v234, 16, v192
	v_and_b32_e32 v235, 0xffff0000, v192
	v_lshlrev_b32_e32 v236, 16, v193
	v_and_b32_e32 v237, 0xffff0000, v193
	v_fma_f32 v238, v44, v234, v230
	v_fma_f32 v239, v45, v235, v231
	v_fma_f32 v240, v46, v236, v232
	v_fma_f32 v241, v47, v237, v233
	v_cvt_pk_bf16_f32 v244, v238, v239
	v_cvt_pk_bf16_f32 v245, v240, v241
	ds_write_b64 v246, v[244:245] offset:13088
	s_waitcnt lgkmcnt(0)
	s_barrier
	ds_read_b128 v[230:233], v247 offset:0
	ds_read_b128 v[234:237], v247 offset:8704
	s_add_u32 s18, s30, 0x40000
	s_addc_u32 s19, s31, 0
	s_waitcnt lgkmcnt(1)
	global_store_dwordx4 v228, v[230:233], s[18:19] sc1
	s_add_u32 s18, s30, 0x50000
	s_addc_u32 s19, s31, 0
	s_waitcnt lgkmcnt(0)
	global_store_dwordx4 v228, v[234:237], s[18:19] sc1
	ds_read_b128 v[230:233], v247 offset:17408
	ds_read_b128 v[234:237], v247 offset:26112
	s_add_u32 s18, s30, 0x60000
	s_addc_u32 s19, s31, 0
	s_waitcnt lgkmcnt(1)
	global_store_dwordx4 v228, v[230:233], s[18:19] sc1
	s_add_u32 s18, s30, 0x70000
	s_addc_u32 s19, s31, 0
	s_waitcnt lgkmcnt(0)
	global_store_dwordx4 v228, v[234:237], s[18:19] sc1
	s_waitcnt vmcnt(0)
	ds_write_b128 v227, v[194:197] offset:0
	ds_write_b128 v227, v[198:201] offset:34816
	ds_write_b128 v227, v[202:205] offset:8704
	ds_write_b128 v227, v[206:209] offset:43520
	ds_write_b128 v227, v[210:213] offset:17408
	ds_write_b128 v227, v[214:217] offset:52224
	ds_write_b128 v227, v[218:221] offset:26112
	ds_write_b128 v227, v[222:225] offset:60928
	s_waitcnt lgkmcnt(0)
	s_barrier
	ds_read_b64 v[194:195], v226 offset:0
	ds_read_b64 v[196:197], v226 offset:34816
	ds_read_b64 v[198:199], v226 offset:32
	ds_read_b64 v[200:201], v226 offset:34848
	ds_read_b64 v[202:203], v226 offset:4352
	ds_read_b64 v[204:205], v226 offset:39168
	ds_read_b64 v[206:207], v226 offset:4384
	ds_read_b64 v[208:209], v226 offset:39200
	ds_read_b64 v[210:211], v226 offset:8704
	ds_read_b64 v[212:213], v226 offset:43520
	ds_read_b64 v[214:215], v226 offset:8736
	ds_read_b64 v[216:217], v226 offset:43552
	ds_read_b64 v[218:219], v226 offset:13056
	ds_read_b64 v[220:221], v226 offset:47872
	ds_read_b64 v[222:223], v226 offset:13088
	ds_read_b64 v[224:225], v226 offset:47904
	s_waitcnt lgkmcnt(14)
	v_lshlrev_b32_e32 v230, 16, v194
	v_and_b32_e32 v231, 0xffff0000, v194
	v_lshlrev_b32_e32 v232, 16, v195
	v_and_b32_e32 v233, 0xffff0000, v195
	v_lshlrev_b32_e32 v234, 16, v196
	v_and_b32_e32 v235, 0xffff0000, v196
	v_lshlrev_b32_e32 v236, 16, v197
	v_and_b32_e32 v237, 0xffff0000, v197
	v_fma_f32 v238, v20, v234, v230
	v_fma_f32 v239, v21, v235, v231
	v_fma_f32 v240, v22, v236, v232
	v_fma_f32 v241, v23, v237, v233
	v_cvt_pk_bf16_f32 v242, v238, v239
	v_cvt_pk_bf16_f32 v243, v240, v241
	ds_write_b64 v246, v[242:243] offset:0
	s_waitcnt lgkmcnt(12)
	v_lshlrev_b32_e32 v230, 16, v198
	v_and_b32_e32 v231, 0xffff0000, v198
	v_lshlrev_b32_e32 v232, 16, v199
	v_and_b32_e32 v233, 0xffff0000, v199
	v_lshlrev_b32_e32 v234, 16, v200
	v_and_b32_e32 v235, 0xffff0000, v200
	v_lshlrev_b32_e32 v236, 16, v201
	v_and_b32_e32 v237, 0xffff0000, v201
	v_fma_f32 v238, v24, v234, v230
	v_fma_f32 v239, v25, v235, v231
	v_fma_f32 v240, v26, v236, v232
	v_fma_f32 v241, v27, v237, v233
	v_cvt_pk_bf16_f32 v244, v238, v239
	v_cvt_pk_bf16_f32 v245, v240, v241
	ds_write_b64 v246, v[244:245] offset:32
	s_waitcnt lgkmcnt(10)
	v_lshlrev_b32_e32 v230, 16, v202
	v_and_b32_e32 v231, 0xffff0000, v202
	v_lshlrev_b32_e32 v232, 16, v203
	v_and_b32_e32 v233, 0xffff0000, v203
	v_lshlrev_b32_e32 v234, 16, v204
	v_and_b32_e32 v235, 0xffff0000, v204
	v_lshlrev_b32_e32 v236, 16, v205
	v_and_b32_e32 v237, 0xffff0000, v205
	v_fma_f32 v238, v28, v234, v230
	v_fma_f32 v239, v29, v235, v231
	v_fma_f32 v240, v30, v236, v232
	v_fma_f32 v241, v31, v237, v233
	v_cvt_pk_bf16_f32 v242, v238, v239
	v_cvt_pk_bf16_f32 v243, v240, v241
	ds_write_b64 v246, v[242:243] offset:4352
	s_waitcnt lgkmcnt(8)
	v_lshlrev_b32_e32 v230, 16, v206
	v_and_b32_e32 v231, 0xffff0000, v206
	v_lshlrev_b32_e32 v232, 16, v207
	v_and_b32_e32 v233, 0xffff0000, v207
	v_lshlrev_b32_e32 v234, 16, v208
	v_and_b32_e32 v235, 0xffff0000, v208
	v_lshlrev_b32_e32 v236, 16, v209
	v_and_b32_e32 v237, 0xffff0000, v209
	v_fma_f32 v238, v16, v234, v230
	v_fma_f32 v239, v17, v235, v231
	v_fma_f32 v240, v18, v236, v232
	v_fma_f32 v241, v19, v237, v233
	v_cvt_pk_bf16_f32 v244, v238, v239
	v_cvt_pk_bf16_f32 v245, v240, v241
	ds_write_b64 v246, v[244:245] offset:4384
	s_waitcnt lgkmcnt(6)
	v_lshlrev_b32_e32 v230, 16, v210
	v_and_b32_e32 v231, 0xffff0000, v210
	v_lshlrev_b32_e32 v232, 16, v211
	v_and_b32_e32 v233, 0xffff0000, v211
	v_lshlrev_b32_e32 v234, 16, v212
	v_and_b32_e32 v235, 0xffff0000, v212
	v_lshlrev_b32_e32 v236, 16, v213
	v_and_b32_e32 v237, 0xffff0000, v213
	v_fma_f32 v238, v0, v234, v230
	v_fma_f32 v239, v1, v235, v231
	v_fma_f32 v240, v2, v236, v232
	v_fma_f32 v241, v3, v237, v233
	v_cvt_pk_bf16_f32 v242, v238, v239
	v_cvt_pk_bf16_f32 v243, v240, v241
	ds_write_b64 v246, v[242:243] offset:8704
	s_waitcnt lgkmcnt(4)
	v_lshlrev_b32_e32 v230, 16, v214
	v_and_b32_e32 v231, 0xffff0000, v214
	v_lshlrev_b32_e32 v232, 16, v215
	v_and_b32_e32 v233, 0xffff0000, v215
	v_lshlrev_b32_e32 v234, 16, v216
	v_and_b32_e32 v235, 0xffff0000, v216
	v_lshlrev_b32_e32 v236, 16, v217
	v_and_b32_e32 v237, 0xffff0000, v217
	v_fma_f32 v238, v4, v234, v230
	v_fma_f32 v239, v5, v235, v231
	v_fma_f32 v240, v6, v236, v232
	v_fma_f32 v241, v7, v237, v233
	v_cvt_pk_bf16_f32 v244, v238, v239
	v_cvt_pk_bf16_f32 v245, v240, v241
	ds_write_b64 v246, v[244:245] offset:8736
	s_waitcnt lgkmcnt(2)
	v_lshlrev_b32_e32 v230, 16, v218
	v_and_b32_e32 v231, 0xffff0000, v218
	v_lshlrev_b32_e32 v232, 16, v219
	v_and_b32_e32 v233, 0xffff0000, v219
	v_lshlrev_b32_e32 v234, 16, v220
	v_and_b32_e32 v235, 0xffff0000, v220
	v_lshlrev_b32_e32 v236, 16, v221
	v_and_b32_e32 v237, 0xffff0000, v221
	v_fma_f32 v238, v8, v234, v230
	v_fma_f32 v239, v9, v235, v231
	v_fma_f32 v240, v10, v236, v232
	v_fma_f32 v241, v11, v237, v233
	v_cvt_pk_bf16_f32 v242, v238, v239
	v_cvt_pk_bf16_f32 v243, v240, v241
	ds_write_b64 v246, v[242:243] offset:13056
	s_waitcnt lgkmcnt(0)
	v_lshlrev_b32_e32 v230, 16, v222
	v_and_b32_e32 v231, 0xffff0000, v222
	v_lshlrev_b32_e32 v232, 16, v223
	v_and_b32_e32 v233, 0xffff0000, v223
	v_lshlrev_b32_e32 v234, 16, v224
	v_and_b32_e32 v235, 0xffff0000, v224
	v_lshlrev_b32_e32 v236, 16, v225
	v_and_b32_e32 v237, 0xffff0000, v225
	v_fma_f32 v238, v12, v234, v230
	v_fma_f32 v239, v13, v235, v231
	v_fma_f32 v240, v14, v236, v232
	v_fma_f32 v241, v15, v237, v233
	v_cvt_pk_bf16_f32 v244, v238, v239
	v_cvt_pk_bf16_f32 v245, v240, v241
	ds_write_b64 v246, v[244:245] offset:13088
	s_waitcnt lgkmcnt(0)
	s_barrier
	ds_read_b128 v[230:233], v247 offset:0
	ds_read_b128 v[234:237], v247 offset:8704
	s_add_u32 s18, s30, 0x40100
	s_addc_u32 s19, s31, 0
	s_waitcnt lgkmcnt(1)
	global_store_dwordx4 v228, v[230:233], s[18:19] sc1
	s_add_u32 s18, s30, 0x50100
	s_addc_u32 s19, s31, 0
	s_waitcnt lgkmcnt(0)
	global_store_dwordx4 v228, v[234:237], s[18:19] sc1
	ds_read_b128 v[230:233], v247 offset:17408
	ds_read_b128 v[234:237], v247 offset:26112
	s_add_u32 s18, s30, 0x60100
	s_addc_u32 s19, s31, 0
	s_waitcnt lgkmcnt(1)
	global_store_dwordx4 v228, v[230:233], s[18:19] sc1
	s_add_u32 s18, s30, 0x70100
	s_addc_u32 s19, s31, 0
	s_waitcnt lgkmcnt(0)
	global_store_dwordx4 v228, v[234:237], s[18:19] sc1
	s_cmpk_lt_i32 s28, 0x400
	s_barrier
	s_cbranch_scc0 .LBB0_1234
